# final RMSNorm row loop: gamma row hoisted into 32 VGPRs (loop invariant), all 8 row-chunk loads issued up front with counted vmcnt(7) waits, stores never waited on; on top of v026
# speedup vs baseline: 1.0112x; 1.0042x over previous
; __device__ __forceinline__ void final_phase(float* x, const float* ssq, const float* gn, bool team) {
;     const int tid = threadIdx.x, lane = tid & 63, wave = tid >> 6; const int gw = blockIdx.x * 8 + wave, NGW = gridDim.x * 8;
;     const int mbeg = team ? my_pm() * 256 + (int)(blockIdx.x >> 6) * 64 + wave : gw, mend = team ? my_pm() * 256 + (int)(blockIdx.x >> 6) * 64 + 64 : M, mstep = team ? 8 : NGW;
;     for (int m = mbeg; m < mend; m += mstep) { float s = ssq[(size_t)m * 32 + (lane & 31)];
; #pragma unroll
;         for (int o = 1; o < 32; o <<= 1) s += __shfl_xor(s, o);
;         const float rs = __builtin_amdgcn_rsqf(s * (1.0f / D) + 1e-6f); f32x4* xr = (f32x4*)(x + (size_t)m * D) + lane; const f32x4* gr = (const f32x4*)gn + lane;
; #pragma unroll
;         for (int j = 0; j < 8; ++j) xr[64 * j] = xr[64 * j] * rs * gr[64 * j]; }
.LBB0_2362:
	v_add_u32_e32 v1, v3, v4
	v_add_u32_e32 v1, 64, v1
	v_mov_b32_e32 v3, 0x4000
	s_waitcnt vmcnt(19)
	v_cndmask_b32_e64 v22, v3, v1, s[88:89]
	v_cmp_lt_i32_e32 vcc, v0, v22
	s_and_saveexec_b64 s[0:1], vcc
	s_cbranch_execz .LBB0_2365
	v_mbcnt_lo_u32_b32 v3, -1, 0
	v_mbcnt_hi_u32_b32 v3, -1, v3
	v_and_b32_e32 v1, 63, v200
	v_and_b32_e32 v4, 64, v3
	v_add_u32_e32 v6, 64, v4
	v_lshlrev_b32_e32 v14, 4, v1
	v_xor_b32_e32 v1, 1, v3
	v_cmp_lt_i32_e32 vcc, v1, v6
	s_load_dwordx4 s[4:7], s[92:93], 0xe8
	v_mov_b32_e32 v15, 0
	v_cndmask_b32_e32 v1, v3, v1, vcc
	v_lshlrev_b32_e32 v23, 2, v1
	v_xor_b32_e32 v1, 2, v3
	v_cmp_lt_i32_e32 vcc, v1, v6
	v_and_b32_e32 v20, 31, v200
	s_waitcnt lgkmcnt(0)
	v_lshl_add_u64 v[4:5], s[4:5], 0, v[14:15]
	v_cndmask_b32_e32 v1, v3, v1, vcc
	v_lshlrev_b32_e32 v24, 2, v1
	v_xor_b32_e32 v1, 4, v3
	v_cmp_lt_i32_e32 vcc, v1, v6
	s_mov_b64 s[2:3], 0x1400
	s_mov_b64 s[0:1], 0x1000
	v_cndmask_b32_e32 v1, v3, v1, vcc
	v_lshlrev_b32_e32 v25, 2, v1
	v_xor_b32_e32 v1, 8, v3
	v_cmp_lt_i32_e32 vcc, v1, v6
	v_lshl_add_u64 v[8:9], v[4:5], 0, s[2:3]
	s_mov_b64 s[2:3], 0x1800
	v_cndmask_b32_e32 v1, v3, v1, vcc
	s_waitcnt vmcnt(18)
	v_lshlrev_b32_e32 v26, 2, v1
	v_xor_b32_e32 v1, 16, v3
	v_cmp_lt_i32_e32 vcc, v1, v6
	v_lshl_add_u64 v[6:7], v[4:5], 0, s[0:1]
	v_lshl_add_u64 v[10:11], v[4:5], 0, s[2:3]
	v_cndmask_b32_e32 v1, v3, v1, vcc
	v_lshlrev_b32_e32 v27, 2, v1
	v_ashrrev_i32_e32 v1, 31, v0
	v_lshlrev_b64 v[16:17], 13, v[0:1]
	v_or_b32_e32 v16, v16, v14
	v_lshlrev_b64 v[18:19], 7, v[0:1]
	v_lshl_add_u64 v[14:15], s[6:7], 0, v[16:17]
	v_lshl_or_b32 v18, v20, 2, v18
	s_mov_b64 s[2:3], 0x1c00
	v_lshl_add_u64 v[14:15], v[14:15], 0, s[0:1]
	v_ashrrev_i32_e32 v3, 31, v2
	v_lshl_add_u64 v[18:19], s[74:75], 0, v[18:19]
	s_mov_b64 s[0:1], 0x200000
	v_lshl_add_u64 v[12:13], v[4:5], 0, s[2:3]
	v_lshlrev_b64 v[16:17], 13, v[2:3]
	v_lshl_add_u64 v[18:19], v[18:19], 0, s[0:1]
	v_lshlrev_b64 v[20:21], 7, v[2:3]
	s_mov_b64 s[0:1], 0
	v_mov_b32_e32 v1, 0x358637bd
	global_load_dwordx4 v[44:47], v[4:5], off
	global_load_dwordx4 v[48:51], v[4:5], off offset:1024
	global_load_dwordx4 v[52:55], v[4:5], off offset:2048
	global_load_dwordx4 v[56:59], v[4:5], off offset:3072
	global_load_dwordx4 v[60:63], v[6:7], off
	global_load_dwordx4 v[64:67], v[8:9], off
	global_load_dwordx4 v[68:71], v[10:11], off
	global_load_dwordx4 v[72:75], v[12:13], off
.LBB0_2364:
	global_load_dword v3, v[18:19], off
	global_load_dwordx4 v[76:79], v[14:15], off offset:-4096
	global_load_dwordx4 v[80:83], v[14:15], off offset:-3072
	global_load_dwordx4 v[84:87], v[14:15], off offset:-2048
	global_load_dwordx4 v[88:91], v[14:15], off offset:-1024
	global_load_dwordx4 v[92:95], v[14:15], off
	global_load_dwordx4 v[96:99], v[14:15], off offset:1024
	global_load_dwordx4 v[100:103], v[14:15], off offset:2048
	global_load_dwordx4 v[104:107], v[14:15], off offset:3072
	v_add_u32_e32 v0, v0, v2
	v_cmp_ge_i32_e32 vcc, v0, v22
	v_lshl_add_u64 v[18:19], v[18:19], 0, v[20:21]
	s_or_b64 s[0:1], vcc, s[0:1]
	s_waitcnt vmcnt(8)
	ds_bpermute_b32 v40, v23, v3
	s_waitcnt lgkmcnt(0)
	v_add_f32_e32 v3, v3, v40
	ds_bpermute_b32 v40, v24, v3
	s_waitcnt lgkmcnt(0)
	v_add_f32_e32 v3, v3, v40
	ds_bpermute_b32 v40, v25, v3
	s_waitcnt lgkmcnt(0)
	v_add_f32_e32 v3, v3, v40
	ds_bpermute_b32 v40, v26, v3
	s_waitcnt lgkmcnt(0)
	v_add_f32_e32 v3, v3, v40
	ds_bpermute_b32 v40, v27, v3
	s_waitcnt lgkmcnt(0)
	v_add_f32_e32 v3, v3, v40
	v_fmamk_f32 v3, v3, 0x3a000000, v1
	v_rsq_f32_e32 v40, v3
	s_waitcnt vmcnt(7)
	v_pk_mul_f32 v[76:77], v[76:77], v[40:41] op_sel_hi:[1,0]
	v_pk_mul_f32 v[78:79], v[78:79], v[40:41] op_sel_hi:[1,0]
	v_pk_mul_f32 v[76:77], v[44:45], v[76:77]
	v_pk_mul_f32 v[78:79], v[46:47], v[78:79]
	global_store_dwordx4 v[14:15], v[76:79], off offset:-4096
	s_waitcnt vmcnt(7)
	v_pk_mul_f32 v[80:81], v[80:81], v[40:41] op_sel_hi:[1,0]
	v_pk_mul_f32 v[82:83], v[82:83], v[40:41] op_sel_hi:[1,0]
	v_pk_mul_f32 v[80:81], v[48:49], v[80:81]
	v_pk_mul_f32 v[82:83], v[50:51], v[82:83]
	global_store_dwordx4 v[14:15], v[80:83], off offset:-3072
	s_waitcnt vmcnt(7)
	v_pk_mul_f32 v[84:85], v[84:85], v[40:41] op_sel_hi:[1,0]
	v_pk_mul_f32 v[86:87], v[86:87], v[40:41] op_sel_hi:[1,0]
	v_pk_mul_f32 v[84:85], v[52:53], v[84:85]
	v_pk_mul_f32 v[86:87], v[54:55], v[86:87]
	global_store_dwordx4 v[14:15], v[84:87], off offset:-2048
	s_waitcnt vmcnt(7)
	v_pk_mul_f32 v[88:89], v[88:89], v[40:41] op_sel_hi:[1,0]
	v_pk_mul_f32 v[90:91], v[90:91], v[40:41] op_sel_hi:[1,0]
	v_pk_mul_f32 v[88:89], v[56:57], v[88:89]
	v_pk_mul_f32 v[90:91], v[58:59], v[90:91]
	global_store_dwordx4 v[14:15], v[88:91], off offset:-1024
	s_waitcnt vmcnt(7)
	v_pk_mul_f32 v[92:93], v[92:93], v[40:41] op_sel_hi:[1,0]
	v_pk_mul_f32 v[94:95], v[94:95], v[40:41] op_sel_hi:[1,0]
	v_pk_mul_f32 v[92:93], v[60:61], v[92:93]
	v_pk_mul_f32 v[94:95], v[62:63], v[94:95]
	global_store_dwordx4 v[14:15], v[92:95], off
	s_waitcnt vmcnt(7)
	v_pk_mul_f32 v[96:97], v[96:97], v[40:41] op_sel_hi:[1,0]
	v_pk_mul_f32 v[98:99], v[98:99], v[40:41] op_sel_hi:[1,0]
	v_pk_mul_f32 v[96:97], v[64:65], v[96:97]
	v_pk_mul_f32 v[98:99], v[66:67], v[98:99]
	global_store_dwordx4 v[14:15], v[96:99], off offset:1024
	s_waitcnt vmcnt(7)
	v_pk_mul_f32 v[100:101], v[100:101], v[40:41] op_sel_hi:[1,0]
	v_pk_mul_f32 v[102:103], v[102:103], v[40:41] op_sel_hi:[1,0]
	v_pk_mul_f32 v[100:101], v[68:69], v[100:101]
	v_pk_mul_f32 v[102:103], v[70:71], v[102:103]
	global_store_dwordx4 v[14:15], v[100:103], off offset:2048
	s_waitcnt vmcnt(7)
	v_pk_mul_f32 v[104:105], v[104:105], v[40:41] op_sel_hi:[1,0]
	v_pk_mul_f32 v[106:107], v[106:107], v[40:41] op_sel_hi:[1,0]
	v_pk_mul_f32 v[104:105], v[72:73], v[104:105]
	v_pk_mul_f32 v[106:107], v[74:75], v[106:107]
	global_store_dwordx4 v[14:15], v[104:107], off offset:3072
	v_lshl_add_u64 v[14:15], v[14:15], 0, v[16:17]
	s_andn2_b64 exec, exec, s[0:1]
	s_cbranch_execnz .LBB0_2364
